# fused-up epilogue: hipcc's original vmcnt counts kept at the channel-group boundary (4 uncounted stash stores replace the 4 merged row stores)
# speedup vs baseline: 1.0049x; 1.0028x over previous
.LBB0_505:
	s_or_b64 exec, exec, s[62:63]
	v_mov_b32_e32 v169, v168
	v_mov_b32_e32 v163, v162
	v_mov_b32_e32 v161, v160
	v_mov_b32_e32 v159, v158
	v_mov_b32_e32 v155, v154
	v_mov_b32_e32 v153, v152
	v_mov_b32_e32 v151, v150
	v_mov_b32_e32 v149, v148
	v_mov_b32_e32 v64, v168
	v_mov_b32_e32 v65, v168
	v_pk_mul_f32 v[62:63], v[62:63], v[64:65]
	v_pk_mul_f32 v[60:61], v[60:61], v[168:169]
	v_pk_mul_f32 v[58:59], v[58:59], v[64:65]
	v_pk_mul_f32 v[56:57], v[56:57], v[168:169]
	v_pk_mul_f32 v[52:53], v[52:53], v[162:163]
	v_pk_mul_f32 v[64:65], v[44:45], v[162:163]
	v_pk_mul_f32 v[48:49], v[48:49], v[160:161]
	v_pk_mul_f32 v[44:45], v[36:37], v[160:161]
	v_pk_mul_f32 v[36:37], v[40:41], v[158:159]
	v_pk_mul_f32 v[32:33], v[32:33], v[158:159]
	v_pk_mul_f32 v[28:29], v[28:29], v[154:155]
	v_pk_mul_f32 v[24:25], v[24:25], v[154:155]
	v_pk_mul_f32 v[120:121], v[20:21], v[152:153]
	v_pk_mul_f32 v[12:13], v[12:13], v[152:153]
	v_pk_mul_f32 v[20:21], v[4:5], v[150:151]
	v_pk_mul_f32 v[4:5], v[8:9], v[148:149]
	v_pk_mul_f32 v[0:1], v[0:1], v[148:149]
	v_pk_mul_f32 v[118:119], v[16:17], v[150:151]
	s_waitcnt vmcnt(8)
	v_mul_f32_dpp v16, v60, v116 row_shr:1 row_mask:0xf bank_mask:0xf bound_ctrl:1
	v_mov_b32_dpp v9, v60 row_shr:2 row_mask:0xf bank_mask:0xf bound_ctrl:1
	s_waitcnt vmcnt(7)
	v_fmac_f32_e32 v16, v60, v114
	v_fmac_f32_e32 v16, v100, v9
	v_add_f32_e32 v16, v112, v16
	v_mul_f32_e32 v9, 0xbfb8aa3b, v16
	v_exp_f32_e32 v17, v9
	s_waitcnt vmcnt(5)
	v_mul_f32_dpp v41, v56, v110 row_shr:1 row_mask:0xf bank_mask:0xf bound_ctrl:1
	v_mov_b32_dpp v40, v56 row_shr:2 row_mask:0xf bank_mask:0xf bound_ctrl:1
	s_waitcnt vmcnt(4)
	v_fmac_f32_e32 v41, v56, v102
	v_add_f32_e32 v17, 1.0, v17
	v_rcp_f32_e32 v17, v17
	v_fmac_f32_e32 v41, v98, v40
	s_waitcnt vmcnt(3)
	v_add_f32_e32 v40, v108, v41
	v_mul_f32_dpp v66, v57, v111 row_shr:1 row_mask:0xf bank_mask:0xf bound_ctrl:1
	v_mul_f32_dpp v41, v61, v117 row_shr:1 row_mask:0xf bank_mask:0xf bound_ctrl:1
	v_mul_f32_e32 v16, v16, v17
	v_mov_b32_dpp v17, v61 row_shr:2 row_mask:0xf bank_mask:0xf bound_ctrl:1
	v_fmac_f32_e32 v41, v61, v115
	v_fmac_f32_e32 v41, v101, v17
	v_add_f32_e32 v17, v113, v41
	v_mul_f32_e32 v41, 0xbfb8aa3b, v17
	v_exp_f32_e32 v41, v41
	v_mul_f32_e32 v16, v40, v16
	v_mov_b32_dpp v40, v57 row_shr:2 row_mask:0xf bank_mask:0xf bound_ctrl:1
	v_fmac_f32_e32 v66, v57, v103
	v_add_f32_e32 v41, 1.0, v41
	v_rcp_f32_e32 v41, v41
	v_fmac_f32_e32 v66, v99, v40
	v_add_f32_e32 v40, v109, v66
	v_or_b32_e32 v8, 18, v146
	v_mul_f32_e32 v17, v17, v41
	v_mul_f32_e32 v17, v40, v17
	v_cvt_pk_bf16_f32 v94, v16, v17
	v_ashrrev_i32_e32 v9, 31, v8
	v_mov_b32_dpp v16, v60 row_ror:1 row_mask:0xf bank_mask:0xf bound_ctrl:1
	v_mov_b32_dpp v17, v60 row_ror:2 row_mask:0xf bank_mask:0xf bound_ctrl:1
	v_mov_b32_dpp v40, v56 row_ror:1 row_mask:0xf bank_mask:0xf bound_ctrl:1
	v_mov_b32_dpp v16, v52 row_shr:1 row_mask:0xf bank_mask:0xf
	v_mul_f32_e32 v16, v116, v16
	v_mov_b32_dpp v17, v52 row_shr:2 row_mask:0xf bank_mask:0xf
	v_fmac_f32_e32 v16, v52, v114
	v_fmac_f32_e32 v16, v100, v17
	v_add_f32_e32 v16, v112, v16
	v_mul_f32_e32 v17, 0xbfb8aa3b, v16
	v_exp_f32_e32 v17, v17
	v_mov_b32_dpp v40, v64 row_shr:1 row_mask:0xf bank_mask:0xf
	v_mov_b32_dpp v41, v56 row_ror:2 row_mask:0xf bank_mask:0xf bound_ctrl:1
	v_mul_f32_e32 v40, v110, v40
	v_add_f32_e32 v17, 1.0, v17
	v_rcp_f32_e32 v17, v17
	v_mov_b32_dpp v41, v64 row_shr:2 row_mask:0xf bank_mask:0xf
	v_fmac_f32_e32 v40, v64, v102
	v_fmac_f32_e32 v40, v98, v41
	v_mul_f32_e32 v16, v16, v17
	v_mov_b32_dpp v17, v61 row_ror:1 row_mask:0xf bank_mask:0xf bound_ctrl:1
	v_add_f32_e32 v40, v108, v40
	v_mul_f32_e32 v16, v40, v16
	v_mov_b32_dpp v17, v53 row_shr:1 row_mask:0xf bank_mask:0xf
	v_mov_b32_dpp v40, v61 row_ror:2 row_mask:0xf bank_mask:0xf bound_ctrl:1
	v_mul_f32_e32 v17, v117, v17
	v_fmac_f32_e32 v17, v53, v115
	v_mov_b32_dpp v40, v53 row_shr:2 row_mask:0xf bank_mask:0xf
	v_fmac_f32_e32 v17, v101, v40
	v_add_f32_e32 v17, v113, v17
	v_mul_f32_e32 v40, 0xbfb8aa3b, v17
	v_exp_f32_e32 v40, v40
	v_mov_b32_dpp v41, v57 row_ror:1 row_mask:0xf bank_mask:0xf bound_ctrl:1
	v_mov_b32_dpp v66, v57 row_ror:2 row_mask:0xf bank_mask:0xf bound_ctrl:1
	v_add_f32_e32 v40, 1.0, v40
	v_mov_b32_dpp v41, v65 row_shr:1 row_mask:0xf bank_mask:0xf
	v_rcp_f32_e32 v40, v40
	v_mul_f32_e32 v41, v111, v41
	v_mov_b32_dpp v66, v65 row_shr:2 row_mask:0xf bank_mask:0xf
	v_fmac_f32_e32 v41, v65, v103
	v_fmac_f32_e32 v41, v99, v66
	v_add_f32_e32 v41, v109, v41
	v_mul_f32_e32 v17, v17, v40
	v_mul_f32_e32 v17, v41, v17
	v_cvt_pk_bf16_f32 v88, v16, v17
	v_mov_b32_dpp v16, v52 row_ror:1 row_mask:0xf bank_mask:0xf bound_ctrl:1
	s_nop 0
	v_mov_b32_dpp v17, v52 row_ror:2 row_mask:0xf bank_mask:0xf bound_ctrl:1
	v_mov_b32_dpp v40, v64 row_ror:1 row_mask:0xf bank_mask:0xf bound_ctrl:1
	v_mov_b32_dpp v16, v48 row_shr:1 row_mask:0xf bank_mask:0xf
	v_mul_f32_e32 v16, v116, v16
	v_mov_b32_dpp v17, v48 row_shr:2 row_mask:0xf bank_mask:0xf
	v_fmac_f32_e32 v16, v48, v114
	v_fmac_f32_e32 v16, v100, v17
	v_add_f32_e32 v16, v112, v16
	v_mul_f32_e32 v17, 0xbfb8aa3b, v16
	v_exp_f32_e32 v17, v17
	v_mov_b32_dpp v40, v44 row_shr:1 row_mask:0xf bank_mask:0xf
	v_mov_b32_dpp v41, v64 row_ror:2 row_mask:0xf bank_mask:0xf bound_ctrl:1
	v_mul_f32_e32 v40, v110, v40
	v_add_f32_e32 v17, 1.0, v17
	v_rcp_f32_e32 v17, v17
	v_mov_b32_dpp v41, v44 row_shr:2 row_mask:0xf bank_mask:0xf
	v_fmac_f32_e32 v40, v44, v102
	v_fmac_f32_e32 v40, v98, v41
	v_mul_f32_e32 v16, v16, v17
	v_mov_b32_dpp v17, v53 row_ror:1 row_mask:0xf bank_mask:0xf bound_ctrl:1
	v_add_f32_e32 v40, v108, v40
	v_mul_f32_e32 v16, v40, v16
	v_mov_b32_dpp v17, v49 row_shr:1 row_mask:0xf bank_mask:0xf
	v_mov_b32_dpp v40, v53 row_ror:2 row_mask:0xf bank_mask:0xf bound_ctrl:1
	v_mul_f32_e32 v17, v117, v17
	v_fmac_f32_e32 v17, v49, v115
	v_mov_b32_dpp v40, v49 row_shr:2 row_mask:0xf bank_mask:0xf
	v_fmac_f32_e32 v17, v101, v40
	v_add_f32_e32 v17, v113, v17
	v_mul_f32_e32 v40, 0xbfb8aa3b, v17
	v_exp_f32_e32 v40, v40
	v_mov_b32_dpp v41, v65 row_ror:1 row_mask:0xf bank_mask:0xf bound_ctrl:1
	v_mov_b32_dpp v52, v65 row_ror:2 row_mask:0xf bank_mask:0xf bound_ctrl:1
	v_add_f32_e32 v40, 1.0, v40
	v_mov_b32_dpp v41, v45 row_shr:1 row_mask:0xf bank_mask:0xf
	v_rcp_f32_e32 v40, v40
	v_mul_f32_e32 v41, v111, v41
	v_mov_b32_dpp v52, v45 row_shr:2 row_mask:0xf bank_mask:0xf
	v_fmac_f32_e32 v41, v45, v103
	v_fmac_f32_e32 v41, v99, v52
	v_add_f32_e32 v41, v109, v41
	v_mul_f32_e32 v17, v17, v40
	v_mul_f32_e32 v17, v41, v17
	v_cvt_pk_bf16_f32 v90, v16, v17
	v_mov_b32_dpp v16, v48 row_ror:1 row_mask:0xf bank_mask:0xf bound_ctrl:1
	s_nop 0
	v_mov_b32_dpp v17, v48 row_ror:2 row_mask:0xf bank_mask:0xf bound_ctrl:1
	v_mov_b32_dpp v40, v44 row_ror:1 row_mask:0xf bank_mask:0xf bound_ctrl:1
	v_mov_b32_dpp v16, v36 row_shr:1 row_mask:0xf bank_mask:0xf
	v_mul_f32_e32 v16, v116, v16
	v_mov_b32_dpp v17, v36 row_shr:2 row_mask:0xf bank_mask:0xf
	v_fmac_f32_e32 v16, v36, v114
	v_fmac_f32_e32 v16, v100, v17
	v_add_f32_e32 v16, v112, v16
	v_mul_f32_e32 v17, 0xbfb8aa3b, v16
	v_exp_f32_e32 v17, v17
	v_mov_b32_dpp v40, v32 row_shr:1 row_mask:0xf bank_mask:0xf
	v_mov_b32_dpp v41, v44 row_ror:2 row_mask:0xf bank_mask:0xf bound_ctrl:1
	v_mul_f32_e32 v40, v110, v40
	v_add_f32_e32 v17, 1.0, v17
	v_rcp_f32_e32 v17, v17
	v_mov_b32_dpp v41, v32 row_shr:2 row_mask:0xf bank_mask:0xf
	v_fmac_f32_e32 v40, v32, v102
	v_fmac_f32_e32 v40, v98, v41
	v_mul_f32_e32 v16, v16, v17
	v_mov_b32_dpp v17, v49 row_ror:1 row_mask:0xf bank_mask:0xf bound_ctrl:1
	v_add_f32_e32 v40, v108, v40
	v_mul_f32_e32 v16, v40, v16
	v_mov_b32_dpp v17, v37 row_shr:1 row_mask:0xf bank_mask:0xf
	v_mov_b32_dpp v40, v49 row_ror:2 row_mask:0xf bank_mask:0xf bound_ctrl:1
	v_mul_f32_e32 v17, v117, v17
	v_fmac_f32_e32 v17, v37, v115
	v_mov_b32_dpp v40, v37 row_shr:2 row_mask:0xf bank_mask:0xf
	v_fmac_f32_e32 v17, v101, v40
	v_add_f32_e32 v17, v113, v17
	v_mul_f32_e32 v40, 0xbfb8aa3b, v17
	v_exp_f32_e32 v40, v40
	v_mov_b32_dpp v41, v45 row_ror:1 row_mask:0xf bank_mask:0xf bound_ctrl:1
	v_mov_b32_dpp v44, v45 row_ror:2 row_mask:0xf bank_mask:0xf bound_ctrl:1
	v_add_f32_e32 v40, 1.0, v40
	v_mov_b32_dpp v41, v33 row_shr:1 row_mask:0xf bank_mask:0xf
	v_rcp_f32_e32 v40, v40
	v_mul_f32_e32 v41, v111, v41
	v_mov_b32_dpp v44, v33 row_shr:2 row_mask:0xf bank_mask:0xf
	v_fmac_f32_e32 v41, v33, v103
	v_fmac_f32_e32 v41, v99, v44
	v_add_f32_e32 v41, v109, v41
	v_mul_f32_e32 v17, v17, v40
	v_mul_f32_e32 v17, v41, v17
	v_cvt_pk_bf16_f32 v92, v16, v17
	v_lshlrev_b64 v[8:9], 2, v[8:9]
	v_lshl_add_u64 v[16:17], s[16:17], 0, v[8:9]
	v_lshl_add_u64 v[52:53], s[28:29], 0, v[8:9]
	global_load_dwordx2 v[40:41], v[164:165], off offset:72
	v_lshl_add_u64 v[44:45], s[24:25], 0, v[8:9]
	global_load_dwordx2 v[64:65], v[166:167], off offset:72
	v_lshl_add_u64 v[48:49], s[26:27], 0, v[8:9]
	global_load_dwordx2 v[68:69], v[16:17], off
	global_load_dwordx2 v[66:67], v[44:45], off
	s_nop 0
	global_load_dwordx2 v[16:17], v[48:49], off
	s_nop 0
	global_load_dwordx2 v[52:53], v[52:53], off
	v_lshl_add_u64 v[44:45], s[30:31], 0, v[8:9]
	v_lshl_add_u64 v[8:9], s[52:53], 0, v[8:9]
	global_load_dwordx2 v[44:45], v[44:45], off
	v_mul_f32_dpp v71, v24, v110 row_shr:1 row_mask:0xf bank_mask:0xf bound_ctrl:1
	global_load_dwordx2 v[48:49], v[8:9], off
	v_mul_f32_dpp v9, v28, v116 row_shr:1 row_mask:0xf bank_mask:0xf bound_ctrl:1
	v_mov_b32_dpp v8, v28 row_shr:2 row_mask:0xf bank_mask:0xf bound_ctrl:1
	v_fmac_f32_e32 v9, v28, v114
	v_fmac_f32_e32 v9, v100, v8
	v_add_f32_e32 v8, v112, v9
	v_mul_f32_e32 v9, 0xbfb8aa3b, v8
	v_exp_f32_e32 v9, v9
	v_mov_b32_dpp v70, v24 row_shr:2 row_mask:0xf bank_mask:0xf bound_ctrl:1
	v_fmac_f32_e32 v71, v24, v102
	v_fmac_f32_e32 v71, v98, v70
	v_add_f32_e32 v9, 1.0, v9
	v_rcp_f32_e32 v9, v9
	v_add_f32_e32 v70, v108, v71
	v_mul_f32_dpp v71, v29, v117 row_shr:1 row_mask:0xf bank_mask:0xf bound_ctrl:1
	v_fmac_f32_e32 v71, v29, v115
	v_mul_f32_e32 v8, v8, v9
	v_mov_b32_dpp v9, v29 row_shr:2 row_mask:0xf bank_mask:0xf bound_ctrl:1
	v_fmac_f32_e32 v71, v101, v9
	v_add_f32_e32 v9, v113, v71
	v_mul_f32_e32 v71, 0xbfb8aa3b, v9
	v_exp_f32_e32 v71, v71
	v_mul_f32_dpp v89, v25, v111 row_shr:1 row_mask:0xf bank_mask:0xf bound_ctrl:1
	v_mul_f32_e32 v8, v70, v8
	v_mov_b32_dpp v70, v25 row_shr:2 row_mask:0xf bank_mask:0xf bound_ctrl:1
	v_add_f32_e32 v71, 1.0, v71
	v_rcp_f32_e32 v71, v71
	v_fmac_f32_e32 v89, v25, v103
	v_fmac_f32_e32 v89, v99, v70
	v_add_f32_e32 v70, v109, v89
	v_mul_f32_e32 v9, v9, v71
	v_mul_f32_e32 v9, v70, v9
	v_cvt_pk_bf16_f32 v70, v8, v9
	v_mov_b32_dpp v8, v28 row_ror:1 row_mask:0xf bank_mask:0xf bound_ctrl:1
	s_nop 0
	v_mov_b32_dpp v9, v28 row_ror:2 row_mask:0xf bank_mask:0xf bound_ctrl:1
	v_mov_b32_dpp v71, v24 row_ror:1 row_mask:0xf bank_mask:0xf bound_ctrl:1
	v_mov_b32_dpp v8, v120 row_shr:1 row_mask:0xf bank_mask:0xf
	v_mul_f32_e32 v8, v116, v8
	v_mov_b32_dpp v9, v120 row_shr:2 row_mask:0xf bank_mask:0xf
	v_fmac_f32_e32 v8, v120, v114
	v_fmac_f32_e32 v8, v100, v9
	v_add_f32_e32 v8, v112, v8
	v_mul_f32_e32 v9, 0xbfb8aa3b, v8
	v_exp_f32_e32 v9, v9
	v_mov_b32_dpp v71, v12 row_shr:1 row_mask:0xf bank_mask:0xf
	v_mov_b32_dpp v89, v24 row_ror:2 row_mask:0xf bank_mask:0xf bound_ctrl:1
	v_mul_f32_e32 v71, v110, v71
	v_add_f32_e32 v9, 1.0, v9
	v_rcp_f32_e32 v9, v9
	v_mov_b32_dpp v89, v12 row_shr:2 row_mask:0xf bank_mask:0xf
	v_fmac_f32_e32 v71, v12, v102
	v_fmac_f32_e32 v71, v98, v89
	v_mul_f32_e32 v8, v8, v9
	v_mov_b32_dpp v9, v29 row_ror:1 row_mask:0xf bank_mask:0xf bound_ctrl:1
	v_add_f32_e32 v71, v108, v71
	v_mul_f32_e32 v8, v71, v8
	v_mov_b32_dpp v9, v121 row_shr:1 row_mask:0xf bank_mask:0xf
	v_mov_b32_dpp v71, v29 row_ror:2 row_mask:0xf bank_mask:0xf bound_ctrl:1
	v_mul_f32_e32 v9, v117, v9
	v_fmac_f32_e32 v9, v121, v115
	v_mov_b32_dpp v71, v121 row_shr:2 row_mask:0xf bank_mask:0xf
	v_fmac_f32_e32 v9, v101, v71
	v_add_f32_e32 v9, v113, v9
	v_mul_f32_e32 v71, 0xbfb8aa3b, v9
	v_exp_f32_e32 v71, v71
	v_mov_b32_dpp v89, v25 row_ror:1 row_mask:0xf bank_mask:0xf bound_ctrl:1
	v_mov_b32_dpp v91, v25 row_ror:2 row_mask:0xf bank_mask:0xf bound_ctrl:1
	v_add_f32_e32 v71, 1.0, v71
	v_mov_b32_dpp v89, v13 row_shr:1 row_mask:0xf bank_mask:0xf
	v_rcp_f32_e32 v71, v71
	v_mul_f32_e32 v89, v111, v89
	v_mov_b32_dpp v91, v13 row_shr:2 row_mask:0xf bank_mask:0xf
	v_fmac_f32_e32 v89, v13, v103
	v_fmac_f32_e32 v89, v99, v91
	v_add_f32_e32 v89, v109, v89
	v_mul_f32_e32 v9, v9, v71
	v_mul_f32_e32 v9, v89, v9
	v_cvt_pk_bf16_f32 v8, v8, v9
	s_nop 1
	v_mov_b32_dpp v9, v120 row_ror:1 row_mask:0xf bank_mask:0xf bound_ctrl:1
	v_mov_b32_dpp v71, v120 row_ror:2 row_mask:0xf bank_mask:0xf bound_ctrl:1
	v_mov_b32_dpp v89, v12 row_ror:1 row_mask:0xf bank_mask:0xf bound_ctrl:1
	v_mov_b32_dpp v9, v118 row_shr:1 row_mask:0xf bank_mask:0xf
	v_mul_f32_e32 v9, v116, v9
	v_mov_b32_dpp v71, v118 row_shr:2 row_mask:0xf bank_mask:0xf
	v_fmac_f32_e32 v9, v118, v114
	v_fmac_f32_e32 v9, v100, v71
	v_add_f32_e32 v9, v112, v9
	v_mul_f32_e32 v71, 0xbfb8aa3b, v9
	v_exp_f32_e32 v71, v71
	v_mov_b32_dpp v89, v20 row_shr:1 row_mask:0xf bank_mask:0xf
	v_mov_b32_dpp v12, v12 row_ror:2 row_mask:0xf bank_mask:0xf bound_ctrl:1
	v_mul_f32_e32 v89, v110, v89
	v_add_f32_e32 v71, 1.0, v71
	v_rcp_f32_e32 v71, v71
	v_mov_b32_dpp v12, v20 row_shr:2 row_mask:0xf bank_mask:0xf
	v_fmac_f32_e32 v89, v20, v102
	v_fmac_f32_e32 v89, v98, v12
	v_add_f32_e32 v12, v108, v89
	v_mul_f32_e32 v9, v9, v71
	v_mul_f32_e32 v9, v12, v9
	v_mov_b32_dpp v12, v121 row_ror:1 row_mask:0xf bank_mask:0xf bound_ctrl:1
	v_mov_b32_dpp v71, v121 row_ror:2 row_mask:0xf bank_mask:0xf bound_ctrl:1
	v_mov_b32_dpp v89, v13 row_ror:1 row_mask:0xf bank_mask:0xf bound_ctrl:1
	v_mov_b32_dpp v12, v119 row_shr:1 row_mask:0xf bank_mask:0xf
	v_mul_f32_e32 v12, v117, v12
	v_mov_b32_dpp v71, v119 row_shr:2 row_mask:0xf bank_mask:0xf
	v_fmac_f32_e32 v12, v119, v115
	v_fmac_f32_e32 v12, v101, v71
	v_add_f32_e32 v12, v113, v12
	v_mul_f32_e32 v71, 0xbfb8aa3b, v12
	v_exp_f32_e32 v71, v71
	v_mov_b32_dpp v89, v21 row_shr:1 row_mask:0xf bank_mask:0xf
	v_mov_b32_dpp v13, v13 row_ror:2 row_mask:0xf bank_mask:0xf bound_ctrl:1
	v_mul_f32_e32 v89, v111, v89
	v_add_f32_e32 v71, 1.0, v71
	v_rcp_f32_e32 v71, v71
	v_mov_b32_dpp v13, v21 row_shr:2 row_mask:0xf bank_mask:0xf
	v_fmac_f32_e32 v89, v21, v103
	v_fmac_f32_e32 v89, v99, v13
	v_add_f32_e32 v13, v109, v89
	v_mul_f32_e32 v12, v12, v71
	v_mul_f32_e32 v12, v13, v12
	v_cvt_pk_bf16_f32 v12, v9, v12
	v_mov_b32_dpp v9, v118 row_ror:1 row_mask:0xf bank_mask:0xf bound_ctrl:1
	v_mov_b32_dpp v13, v118 row_ror:2 row_mask:0xf bank_mask:0xf bound_ctrl:1
	v_mov_b32_dpp v71, v20 row_ror:1 row_mask:0xf bank_mask:0xf bound_ctrl:1
	v_mov_b32_dpp v9, v4 row_shr:1 row_mask:0xf bank_mask:0xf
	v_mul_f32_e32 v9, v116, v9
	v_mov_b32_dpp v13, v4 row_shr:2 row_mask:0xf bank_mask:0xf
	v_fmac_f32_e32 v9, v4, v114
	v_fmac_f32_e32 v9, v100, v13
	v_add_f32_e32 v9, v112, v9
	v_mul_f32_e32 v13, 0xbfb8aa3b, v9
	v_exp_f32_e32 v13, v13
	v_mov_b32_dpp v71, v0 row_shr:1 row_mask:0xf bank_mask:0xf
	v_mov_b32_dpp v20, v20 row_ror:2 row_mask:0xf bank_mask:0xf bound_ctrl:1
	v_mul_f32_e32 v71, v110, v71
	v_add_f32_e32 v13, 1.0, v13
	v_rcp_f32_e32 v13, v13
	v_mov_b32_dpp v20, v0 row_shr:2 row_mask:0xf bank_mask:0xf
	v_fmac_f32_e32 v71, v0, v102
	v_fmac_f32_e32 v71, v98, v20
	v_mul_f32_e32 v9, v9, v13
	v_mov_b32_dpp v13, v119 row_ror:1 row_mask:0xf bank_mask:0xf bound_ctrl:1
	v_add_f32_e32 v20, v108, v71
	v_mul_f32_e32 v9, v20, v9
	v_mov_b32_dpp v13, v5 row_shr:1 row_mask:0xf bank_mask:0xf
	v_mov_b32_dpp v20, v119 row_ror:2 row_mask:0xf bank_mask:0xf bound_ctrl:1
	v_mul_f32_e32 v13, v117, v13
	v_fmac_f32_e32 v13, v5, v115
	v_mov_b32_dpp v20, v5 row_shr:2 row_mask:0xf bank_mask:0xf
	v_fmac_f32_e32 v13, v101, v20
	v_add_f32_e32 v13, v113, v13
	v_mul_f32_e32 v20, 0xbfb8aa3b, v13
	v_exp_f32_e32 v20, v20
	v_mov_b32_dpp v71, v21 row_ror:1 row_mask:0xf bank_mask:0xf bound_ctrl:1
	v_mov_b32_dpp v21, v21 row_ror:2 row_mask:0xf bank_mask:0xf bound_ctrl:1
	v_add_f32_e32 v20, 1.0, v20
	v_mov_b32_dpp v71, v1 row_shr:1 row_mask:0xf bank_mask:0xf
	v_rcp_f32_e32 v20, v20
	v_mul_f32_e32 v71, v111, v71
	v_mov_b32_dpp v21, v1 row_shr:2 row_mask:0xf bank_mask:0xf
	v_fmac_f32_e32 v71, v1, v103
	v_fmac_f32_e32 v71, v99, v21
	v_add_f32_e32 v21, v109, v71
	v_mul_f32_e32 v13, v13, v20
	v_mul_f32_e32 v13, v21, v13
	v_cvt_pk_bf16_f32 v20, v9, v13
	s_waitcnt vmcnt(5)
	s_nop 0
	v_mul_f32_dpp v13, v62, v68 row_shr:1 row_mask:0xf bank_mask:0xf bound_ctrl:1
	v_mov_b32_dpp v9, v62 row_shr:2 row_mask:0xf bank_mask:0xf bound_ctrl:1
	s_waitcnt vmcnt(4)
	v_fmac_f32_e32 v13, v62, v66
	v_fmac_f32_e32 v13, v40, v9
	v_add_f32_e32 v9, v64, v13
	v_mul_f32_e32 v13, 0xbfb8aa3b, v9
	v_exp_f32_e32 v13, v13
	s_waitcnt vmcnt(2)
	v_mul_f32_dpp v71, v58, v52 row_shr:1 row_mask:0xf bank_mask:0xf bound_ctrl:1
	v_mov_b32_dpp v21, v58 row_shr:2 row_mask:0xf bank_mask:0xf bound_ctrl:1
	s_waitcnt vmcnt(1)
	v_fmac_f32_e32 v71, v58, v44
	v_add_f32_e32 v13, 1.0, v13
	v_rcp_f32_e32 v13, v13
	v_fmac_f32_e32 v71, v16, v21
	s_waitcnt vmcnt(0)
	v_add_f32_e32 v21, v48, v71
	v_mul_f32_dpp v89, v59, v53 row_shr:1 row_mask:0xf bank_mask:0xf bound_ctrl:1
	v_mul_f32_dpp v71, v63, v69 row_shr:1 row_mask:0xf bank_mask:0xf bound_ctrl:1
	v_mul_f32_e32 v9, v9, v13
	v_mov_b32_dpp v13, v63 row_shr:2 row_mask:0xf bank_mask:0xf bound_ctrl:1
	v_fmac_f32_e32 v71, v63, v67
	v_fmac_f32_e32 v71, v41, v13
	v_add_f32_e32 v13, v65, v71
	v_mul_f32_e32 v71, 0xbfb8aa3b, v13
	v_exp_f32_e32 v71, v71
	v_mul_f32_e32 v9, v21, v9
	v_mov_b32_dpp v21, v59 row_shr:2 row_mask:0xf bank_mask:0xf bound_ctrl:1
	v_fmac_f32_e32 v89, v59, v45
	v_add_f32_e32 v71, 1.0, v71
	v_rcp_f32_e32 v71, v71
	v_fmac_f32_e32 v89, v17, v21
	v_add_f32_e32 v21, v49, v89
	v_mul_f32_e32 v13, v13, v71
	v_mul_f32_e32 v13, v21, v13
	v_cvt_pk_bf16_f32 v95, v9, v13
	s_and_saveexec_b64 s[62:63], s[2:3]
	s_xor_b64 s[62:63], exec, s[62:63]
	s_cbranch_execz .LBB0_507
	v_mov_b64_e32 v[80:81], s[48:49]
	v_mad_i64_i32 v[80:81], s[64:65], v156, s93, v[80:81]
	v_lshl_add_u64 v[80:81], v[146:147], 1, v[80:81]
	v_mov_b32_e32 v232, v251
	v_mov_b32_e32 v233, v252
	v_mov_b32_e32 v234, v94
	v_mov_b32_e32 v235, v95
	s_nop 1
	v_permlane16_swap_b32_e32 v232, v234
	v_permlane16_swap_b32_e32 v233, v235
	v_lshl_add_u64 v[236:237], v[80:81], 0, v[238:239]
	global_store_dwordx4 v[236:237], v[232:235], off
	s_nop 1

.LBB0_1226:
	s_or_b64 exec, exec, s[56:57]
	v_mov_b32_e32 v165, v164
	v_mov_b32_e32 v163, v162
	v_mov_b32_e32 v161, v160
	v_mov_b32_e32 v159, v158
	v_mov_b32_e32 v155, v154
	v_mov_b32_e32 v153, v152
	v_mov_b32_e32 v151, v150
	v_mov_b32_e32 v149, v148
	v_mov_b32_e32 v64, v164
	v_mov_b32_e32 v65, v164
	v_pk_mul_f32 v[62:63], v[62:63], v[64:65]
	v_pk_mul_f32 v[60:61], v[60:61], v[164:165]
	v_pk_mul_f32 v[58:59], v[58:59], v[64:65]
	v_pk_mul_f32 v[56:57], v[56:57], v[164:165]
	v_pk_mul_f32 v[52:53], v[52:53], v[162:163]
	v_pk_mul_f32 v[64:65], v[44:45], v[162:163]
	v_pk_mul_f32 v[48:49], v[48:49], v[160:161]
	v_pk_mul_f32 v[44:45], v[36:37], v[160:161]
	v_pk_mul_f32 v[36:37], v[40:41], v[158:159]
	v_pk_mul_f32 v[32:33], v[32:33], v[158:159]
	v_pk_mul_f32 v[28:29], v[28:29], v[154:155]
	v_pk_mul_f32 v[24:25], v[24:25], v[154:155]
	v_pk_mul_f32 v[120:121], v[20:21], v[152:153]
	v_pk_mul_f32 v[12:13], v[12:13], v[152:153]
	v_pk_mul_f32 v[20:21], v[4:5], v[150:151]
	v_pk_mul_f32 v[4:5], v[8:9], v[148:149]
	v_pk_mul_f32 v[0:1], v[0:1], v[148:149]
	v_pk_mul_f32 v[118:119], v[16:17], v[150:151]
	s_waitcnt vmcnt(9)
	v_mul_f32_dpp v16, v60, v116 row_shr:1 row_mask:0xf bank_mask:0xf bound_ctrl:1
	v_mov_b32_dpp v9, v60 row_shr:2 row_mask:0xf bank_mask:0xf bound_ctrl:1
	s_waitcnt vmcnt(8)
	v_fmac_f32_e32 v16, v60, v114
	v_fmac_f32_e32 v16, v110, v9
	s_waitcnt vmcnt(7)
	v_add_f32_e32 v16, v112, v16
	v_mul_f32_e32 v9, 0xbfb8aa3b, v16
	v_exp_f32_e32 v17, v9
	s_waitcnt vmcnt(5)
	v_mul_f32_dpp v41, v56, v108 row_shr:1 row_mask:0xf bank_mask:0xf bound_ctrl:1
	v_mov_b32_dpp v40, v56 row_shr:2 row_mask:0xf bank_mask:0xf bound_ctrl:1
	s_waitcnt vmcnt(4)
	v_fmac_f32_e32 v41, v56, v100
	v_add_f32_e32 v17, 1.0, v17
	v_rcp_f32_e32 v17, v17
	v_fmac_f32_e32 v41, v98, v40
	s_waitcnt vmcnt(3)
	v_add_f32_e32 v40, v102, v41
	v_mul_f32_dpp v66, v57, v109 row_shr:1 row_mask:0xf bank_mask:0xf bound_ctrl:1
	v_mul_f32_dpp v41, v61, v117 row_shr:1 row_mask:0xf bank_mask:0xf bound_ctrl:1
	v_mul_f32_e32 v16, v16, v17
	v_mov_b32_dpp v17, v61 row_shr:2 row_mask:0xf bank_mask:0xf bound_ctrl:1
	v_fmac_f32_e32 v41, v61, v115
	v_fmac_f32_e32 v41, v111, v17
	v_add_f32_e32 v17, v113, v41
	v_mul_f32_e32 v41, 0xbfb8aa3b, v17
	v_exp_f32_e32 v41, v41
	v_mul_f32_e32 v16, v40, v16
	v_mov_b32_dpp v40, v57 row_shr:2 row_mask:0xf bank_mask:0xf bound_ctrl:1
	v_fmac_f32_e32 v66, v57, v101
	v_add_f32_e32 v41, 1.0, v41
	v_rcp_f32_e32 v41, v41
	v_fmac_f32_e32 v66, v99, v40
	v_add_f32_e32 v40, v103, v66
	v_or_b32_e32 v8, 18, v146
	v_mul_f32_e32 v17, v17, v41
	v_mul_f32_e32 v17, v40, v17
	v_cvt_pk_bf16_f32 v94, v16, v17
	v_ashrrev_i32_e32 v9, 31, v8
	v_mov_b32_dpp v16, v60 row_ror:1 row_mask:0xf bank_mask:0xf bound_ctrl:1
	v_mov_b32_dpp v17, v60 row_ror:2 row_mask:0xf bank_mask:0xf bound_ctrl:1
	v_mov_b32_dpp v40, v56 row_ror:1 row_mask:0xf bank_mask:0xf bound_ctrl:1
	v_mov_b32_dpp v16, v52 row_shr:1 row_mask:0xf bank_mask:0xf
	v_mul_f32_e32 v16, v116, v16
	v_mov_b32_dpp v17, v52 row_shr:2 row_mask:0xf bank_mask:0xf
	v_fmac_f32_e32 v16, v52, v114
	v_fmac_f32_e32 v16, v110, v17
	v_add_f32_e32 v16, v112, v16
	v_mul_f32_e32 v17, 0xbfb8aa3b, v16
	v_exp_f32_e32 v17, v17
	v_mov_b32_dpp v40, v64 row_shr:1 row_mask:0xf bank_mask:0xf
	v_mov_b32_dpp v41, v56 row_ror:2 row_mask:0xf bank_mask:0xf bound_ctrl:1
	v_mul_f32_e32 v40, v108, v40
	v_add_f32_e32 v17, 1.0, v17
	v_rcp_f32_e32 v17, v17
	v_mov_b32_dpp v41, v64 row_shr:2 row_mask:0xf bank_mask:0xf
	v_fmac_f32_e32 v40, v64, v100
	v_fmac_f32_e32 v40, v98, v41
	v_mul_f32_e32 v16, v16, v17
	v_mov_b32_dpp v17, v61 row_ror:1 row_mask:0xf bank_mask:0xf bound_ctrl:1
	v_add_f32_e32 v40, v102, v40
	v_mul_f32_e32 v16, v40, v16
	v_mov_b32_dpp v17, v53 row_shr:1 row_mask:0xf bank_mask:0xf
	v_mov_b32_dpp v40, v61 row_ror:2 row_mask:0xf bank_mask:0xf bound_ctrl:1
	v_mul_f32_e32 v17, v117, v17
	v_fmac_f32_e32 v17, v53, v115
	v_mov_b32_dpp v40, v53 row_shr:2 row_mask:0xf bank_mask:0xf
	v_fmac_f32_e32 v17, v111, v40
	v_add_f32_e32 v17, v113, v17
	v_mul_f32_e32 v40, 0xbfb8aa3b, v17
	v_exp_f32_e32 v40, v40
	v_mov_b32_dpp v41, v57 row_ror:1 row_mask:0xf bank_mask:0xf bound_ctrl:1
	v_mov_b32_dpp v66, v57 row_ror:2 row_mask:0xf bank_mask:0xf bound_ctrl:1
	v_add_f32_e32 v40, 1.0, v40
	v_mov_b32_dpp v41, v65 row_shr:1 row_mask:0xf bank_mask:0xf
	v_rcp_f32_e32 v40, v40
	v_mul_f32_e32 v41, v109, v41
	v_mov_b32_dpp v66, v65 row_shr:2 row_mask:0xf bank_mask:0xf
	v_fmac_f32_e32 v41, v65, v101
	v_fmac_f32_e32 v41, v99, v66
	v_add_f32_e32 v41, v103, v41
	v_mul_f32_e32 v17, v17, v40
	v_mul_f32_e32 v17, v41, v17
	v_cvt_pk_bf16_f32 v88, v16, v17
	v_mov_b32_dpp v16, v52 row_ror:1 row_mask:0xf bank_mask:0xf bound_ctrl:1
	s_nop 0
	v_mov_b32_dpp v17, v52 row_ror:2 row_mask:0xf bank_mask:0xf bound_ctrl:1
	v_mov_b32_dpp v40, v64 row_ror:1 row_mask:0xf bank_mask:0xf bound_ctrl:1
	v_mov_b32_dpp v16, v48 row_shr:1 row_mask:0xf bank_mask:0xf
	v_mul_f32_e32 v16, v116, v16
	v_mov_b32_dpp v17, v48 row_shr:2 row_mask:0xf bank_mask:0xf
	v_fmac_f32_e32 v16, v48, v114
	v_fmac_f32_e32 v16, v110, v17
	v_add_f32_e32 v16, v112, v16
	v_mul_f32_e32 v17, 0xbfb8aa3b, v16
	v_exp_f32_e32 v17, v17
	v_mov_b32_dpp v40, v44 row_shr:1 row_mask:0xf bank_mask:0xf
	v_mov_b32_dpp v41, v64 row_ror:2 row_mask:0xf bank_mask:0xf bound_ctrl:1
	v_mul_f32_e32 v40, v108, v40
	v_add_f32_e32 v17, 1.0, v17
	v_rcp_f32_e32 v17, v17
	v_mov_b32_dpp v41, v44 row_shr:2 row_mask:0xf bank_mask:0xf
	v_fmac_f32_e32 v40, v44, v100
	v_fmac_f32_e32 v40, v98, v41
	v_mul_f32_e32 v16, v16, v17
	v_mov_b32_dpp v17, v53 row_ror:1 row_mask:0xf bank_mask:0xf bound_ctrl:1
	v_add_f32_e32 v40, v102, v40
	v_mul_f32_e32 v16, v40, v16
	v_mov_b32_dpp v17, v49 row_shr:1 row_mask:0xf bank_mask:0xf
	v_mov_b32_dpp v40, v53 row_ror:2 row_mask:0xf bank_mask:0xf bound_ctrl:1
	v_mul_f32_e32 v17, v117, v17
	v_fmac_f32_e32 v17, v49, v115
	v_mov_b32_dpp v40, v49 row_shr:2 row_mask:0xf bank_mask:0xf
	v_fmac_f32_e32 v17, v111, v40
	v_add_f32_e32 v17, v113, v17
	v_mul_f32_e32 v40, 0xbfb8aa3b, v17
	v_exp_f32_e32 v40, v40
	v_mov_b32_dpp v41, v65 row_ror:1 row_mask:0xf bank_mask:0xf bound_ctrl:1
	v_mov_b32_dpp v52, v65 row_ror:2 row_mask:0xf bank_mask:0xf bound_ctrl:1
	v_add_f32_e32 v40, 1.0, v40
	v_mov_b32_dpp v41, v45 row_shr:1 row_mask:0xf bank_mask:0xf
	v_rcp_f32_e32 v40, v40
	v_mul_f32_e32 v41, v109, v41
	v_mov_b32_dpp v52, v45 row_shr:2 row_mask:0xf bank_mask:0xf
	v_fmac_f32_e32 v41, v45, v101
	v_fmac_f32_e32 v41, v99, v52
	v_add_f32_e32 v41, v103, v41
	v_mul_f32_e32 v17, v17, v40
	v_mul_f32_e32 v17, v41, v17
	v_cvt_pk_bf16_f32 v90, v16, v17
	v_mov_b32_dpp v16, v48 row_ror:1 row_mask:0xf bank_mask:0xf bound_ctrl:1
	s_nop 0
	v_mov_b32_dpp v17, v48 row_ror:2 row_mask:0xf bank_mask:0xf bound_ctrl:1
	v_mov_b32_dpp v40, v44 row_ror:1 row_mask:0xf bank_mask:0xf bound_ctrl:1
	v_mov_b32_dpp v16, v36 row_shr:1 row_mask:0xf bank_mask:0xf
	v_mul_f32_e32 v16, v116, v16
	v_mov_b32_dpp v17, v36 row_shr:2 row_mask:0xf bank_mask:0xf
	v_fmac_f32_e32 v16, v36, v114
	v_fmac_f32_e32 v16, v110, v17
	v_add_f32_e32 v16, v112, v16
	v_mul_f32_e32 v17, 0xbfb8aa3b, v16
	v_exp_f32_e32 v17, v17
	v_mov_b32_dpp v40, v32 row_shr:1 row_mask:0xf bank_mask:0xf
	v_mov_b32_dpp v41, v44 row_ror:2 row_mask:0xf bank_mask:0xf bound_ctrl:1
	v_mul_f32_e32 v40, v108, v40
	v_add_f32_e32 v17, 1.0, v17
	v_rcp_f32_e32 v17, v17
	v_mov_b32_dpp v41, v32 row_shr:2 row_mask:0xf bank_mask:0xf
	v_fmac_f32_e32 v40, v32, v100
	v_fmac_f32_e32 v40, v98, v41
	v_mul_f32_e32 v16, v16, v17
	v_mov_b32_dpp v17, v49 row_ror:1 row_mask:0xf bank_mask:0xf bound_ctrl:1
	v_add_f32_e32 v40, v102, v40
	v_mul_f32_e32 v16, v40, v16
	v_mov_b32_dpp v17, v37 row_shr:1 row_mask:0xf bank_mask:0xf
	v_mov_b32_dpp v40, v49 row_ror:2 row_mask:0xf bank_mask:0xf bound_ctrl:1
	v_mul_f32_e32 v17, v117, v17
	v_fmac_f32_e32 v17, v37, v115
	v_mov_b32_dpp v40, v37 row_shr:2 row_mask:0xf bank_mask:0xf
	v_fmac_f32_e32 v17, v111, v40
	v_add_f32_e32 v17, v113, v17
	v_mul_f32_e32 v40, 0xbfb8aa3b, v17
	v_exp_f32_e32 v40, v40
	v_mov_b32_dpp v41, v45 row_ror:1 row_mask:0xf bank_mask:0xf bound_ctrl:1
	v_mov_b32_dpp v44, v45 row_ror:2 row_mask:0xf bank_mask:0xf bound_ctrl:1
	v_add_f32_e32 v40, 1.0, v40
	v_mov_b32_dpp v41, v33 row_shr:1 row_mask:0xf bank_mask:0xf
	v_rcp_f32_e32 v40, v40
	v_mul_f32_e32 v41, v109, v41
	v_mov_b32_dpp v44, v33 row_shr:2 row_mask:0xf bank_mask:0xf
	v_fmac_f32_e32 v41, v33, v101
	v_fmac_f32_e32 v41, v99, v44
	v_add_f32_e32 v41, v103, v41
	v_mul_f32_e32 v17, v17, v40
	v_mul_f32_e32 v17, v41, v17
	v_cvt_pk_bf16_f32 v92, v16, v17
	v_lshlrev_b64 v[8:9], 2, v[8:9]
	v_lshl_add_u64 v[16:17], s[16:17], 0, v[8:9]
	v_lshl_add_u64 v[40:41], s[8:9], 0, v[8:9]
	v_lshl_add_u64 v[44:45], s[24:25], 0, v[8:9]
	global_load_dwordx2 v[52:53], v[16:17], off
	global_load_dwordx2 v[68:69], v[40:41], off
	global_load_dwordx2 v[66:67], v[44:45], off
	v_lshl_add_u64 v[16:17], s[18:19], 0, v[8:9]
	global_load_dwordx2 v[64:65], v[16:17], off
	v_lshl_add_u64 v[16:17], s[26:27], 0, v[8:9]
	v_lshl_add_u64 v[40:41], s[28:29], 0, v[8:9]
	v_lshl_add_u64 v[44:45], s[30:31], 0, v[8:9]
	global_load_dwordx2 v[16:17], v[16:17], off
	s_nop 0
	global_load_dwordx2 v[48:49], v[40:41], off
	s_nop 0
	global_load_dwordx2 v[40:41], v[44:45], off
	v_lshl_add_u64 v[8:9], s[42:43], 0, v[8:9]
	global_load_dwordx2 v[44:45], v[8:9], off
	v_mul_f32_dpp v71, v24, v108 row_shr:1 row_mask:0xf bank_mask:0xf bound_ctrl:1
	v_mul_f32_dpp v9, v28, v116 row_shr:1 row_mask:0xf bank_mask:0xf bound_ctrl:1
	v_mov_b32_dpp v8, v28 row_shr:2 row_mask:0xf bank_mask:0xf bound_ctrl:1
	v_fmac_f32_e32 v9, v28, v114
	v_fmac_f32_e32 v9, v110, v8
	v_add_f32_e32 v8, v112, v9
	v_mul_f32_e32 v9, 0xbfb8aa3b, v8
	v_exp_f32_e32 v9, v9
	v_mov_b32_dpp v70, v24 row_shr:2 row_mask:0xf bank_mask:0xf bound_ctrl:1
	v_fmac_f32_e32 v71, v24, v100
	v_fmac_f32_e32 v71, v98, v70
	v_add_f32_e32 v9, 1.0, v9
	v_rcp_f32_e32 v9, v9
	v_add_f32_e32 v70, v102, v71
	v_mul_f32_dpp v71, v29, v117 row_shr:1 row_mask:0xf bank_mask:0xf bound_ctrl:1
	v_fmac_f32_e32 v71, v29, v115
	v_mul_f32_e32 v8, v8, v9
	v_mov_b32_dpp v9, v29 row_shr:2 row_mask:0xf bank_mask:0xf bound_ctrl:1
	v_fmac_f32_e32 v71, v111, v9
	v_add_f32_e32 v9, v113, v71
	v_mul_f32_e32 v71, 0xbfb8aa3b, v9
	v_exp_f32_e32 v71, v71
	v_mul_f32_dpp v89, v25, v109 row_shr:1 row_mask:0xf bank_mask:0xf bound_ctrl:1
	v_mul_f32_e32 v8, v70, v8
	v_mov_b32_dpp v70, v25 row_shr:2 row_mask:0xf bank_mask:0xf bound_ctrl:1
	v_add_f32_e32 v71, 1.0, v71
	v_rcp_f32_e32 v71, v71
	v_fmac_f32_e32 v89, v25, v101
	v_fmac_f32_e32 v89, v99, v70
	v_add_f32_e32 v70, v103, v89
	v_mul_f32_e32 v9, v9, v71
	v_mul_f32_e32 v9, v70, v9
	v_cvt_pk_bf16_f32 v70, v8, v9
	v_mov_b32_dpp v8, v28 row_ror:1 row_mask:0xf bank_mask:0xf bound_ctrl:1
	s_nop 0
	v_mov_b32_dpp v9, v28 row_ror:2 row_mask:0xf bank_mask:0xf bound_ctrl:1
	v_mov_b32_dpp v71, v24 row_ror:1 row_mask:0xf bank_mask:0xf bound_ctrl:1
	v_mov_b32_dpp v8, v120 row_shr:1 row_mask:0xf bank_mask:0xf
	v_mul_f32_e32 v8, v116, v8
	v_mov_b32_dpp v9, v120 row_shr:2 row_mask:0xf bank_mask:0xf
	v_fmac_f32_e32 v8, v120, v114
	v_fmac_f32_e32 v8, v110, v9
	v_add_f32_e32 v8, v112, v8
	v_mul_f32_e32 v9, 0xbfb8aa3b, v8
	v_exp_f32_e32 v9, v9
	v_mov_b32_dpp v71, v12 row_shr:1 row_mask:0xf bank_mask:0xf
	v_mov_b32_dpp v89, v24 row_ror:2 row_mask:0xf bank_mask:0xf bound_ctrl:1
	v_mul_f32_e32 v71, v108, v71
	v_add_f32_e32 v9, 1.0, v9
	v_rcp_f32_e32 v9, v9
	v_mov_b32_dpp v89, v12 row_shr:2 row_mask:0xf bank_mask:0xf
	v_fmac_f32_e32 v71, v12, v100
	v_fmac_f32_e32 v71, v98, v89
	v_mul_f32_e32 v8, v8, v9
	v_mov_b32_dpp v9, v29 row_ror:1 row_mask:0xf bank_mask:0xf bound_ctrl:1
	v_add_f32_e32 v71, v102, v71
	v_mul_f32_e32 v8, v71, v8
	v_mov_b32_dpp v9, v121 row_shr:1 row_mask:0xf bank_mask:0xf
	v_mov_b32_dpp v71, v29 row_ror:2 row_mask:0xf bank_mask:0xf bound_ctrl:1
	v_mul_f32_e32 v9, v117, v9
	v_fmac_f32_e32 v9, v121, v115
	v_mov_b32_dpp v71, v121 row_shr:2 row_mask:0xf bank_mask:0xf
	v_fmac_f32_e32 v9, v111, v71
	v_add_f32_e32 v9, v113, v9
	v_mul_f32_e32 v71, 0xbfb8aa3b, v9
	v_exp_f32_e32 v71, v71
	v_mov_b32_dpp v89, v25 row_ror:1 row_mask:0xf bank_mask:0xf bound_ctrl:1
	v_mov_b32_dpp v91, v25 row_ror:2 row_mask:0xf bank_mask:0xf bound_ctrl:1
	v_add_f32_e32 v71, 1.0, v71
	v_mov_b32_dpp v89, v13 row_shr:1 row_mask:0xf bank_mask:0xf
	v_rcp_f32_e32 v71, v71
	v_mul_f32_e32 v89, v109, v89
	v_mov_b32_dpp v91, v13 row_shr:2 row_mask:0xf bank_mask:0xf
	v_fmac_f32_e32 v89, v13, v101
	v_fmac_f32_e32 v89, v99, v91
	v_add_f32_e32 v89, v103, v89
	v_mul_f32_e32 v9, v9, v71
	v_mul_f32_e32 v9, v89, v9
	v_cvt_pk_bf16_f32 v8, v8, v9
	s_nop 1
	v_mov_b32_dpp v9, v120 row_ror:1 row_mask:0xf bank_mask:0xf bound_ctrl:1
	v_mov_b32_dpp v71, v120 row_ror:2 row_mask:0xf bank_mask:0xf bound_ctrl:1
	v_mov_b32_dpp v89, v12 row_ror:1 row_mask:0xf bank_mask:0xf bound_ctrl:1
	v_mov_b32_dpp v9, v118 row_shr:1 row_mask:0xf bank_mask:0xf
	v_mul_f32_e32 v9, v116, v9
	v_mov_b32_dpp v71, v118 row_shr:2 row_mask:0xf bank_mask:0xf
	v_fmac_f32_e32 v9, v118, v114
	v_fmac_f32_e32 v9, v110, v71
	v_add_f32_e32 v9, v112, v9
	v_mul_f32_e32 v71, 0xbfb8aa3b, v9
	v_exp_f32_e32 v71, v71
	v_mov_b32_dpp v89, v20 row_shr:1 row_mask:0xf bank_mask:0xf
	v_mov_b32_dpp v12, v12 row_ror:2 row_mask:0xf bank_mask:0xf bound_ctrl:1
	v_mul_f32_e32 v89, v108, v89
	v_add_f32_e32 v71, 1.0, v71
	v_rcp_f32_e32 v71, v71
	v_mov_b32_dpp v12, v20 row_shr:2 row_mask:0xf bank_mask:0xf
	v_fmac_f32_e32 v89, v20, v100
	v_fmac_f32_e32 v89, v98, v12
	v_add_f32_e32 v12, v102, v89
	v_mul_f32_e32 v9, v9, v71
	v_mul_f32_e32 v9, v12, v9
	v_mov_b32_dpp v12, v121 row_ror:1 row_mask:0xf bank_mask:0xf bound_ctrl:1
	v_mov_b32_dpp v71, v121 row_ror:2 row_mask:0xf bank_mask:0xf bound_ctrl:1
	v_mov_b32_dpp v89, v13 row_ror:1 row_mask:0xf bank_mask:0xf bound_ctrl:1
	v_mov_b32_dpp v12, v119 row_shr:1 row_mask:0xf bank_mask:0xf
	v_mul_f32_e32 v12, v117, v12
	v_mov_b32_dpp v71, v119 row_shr:2 row_mask:0xf bank_mask:0xf
	v_fmac_f32_e32 v12, v119, v115
	v_fmac_f32_e32 v12, v111, v71
	v_add_f32_e32 v12, v113, v12
	v_mul_f32_e32 v71, 0xbfb8aa3b, v12
	v_exp_f32_e32 v71, v71
	v_mov_b32_dpp v89, v21 row_shr:1 row_mask:0xf bank_mask:0xf
	v_mov_b32_dpp v13, v13 row_ror:2 row_mask:0xf bank_mask:0xf bound_ctrl:1
	v_mul_f32_e32 v89, v109, v89
	v_add_f32_e32 v71, 1.0, v71
	v_rcp_f32_e32 v71, v71
	v_mov_b32_dpp v13, v21 row_shr:2 row_mask:0xf bank_mask:0xf
	v_fmac_f32_e32 v89, v21, v101
	v_fmac_f32_e32 v89, v99, v13
	v_add_f32_e32 v13, v103, v89
	v_mul_f32_e32 v12, v12, v71
	v_mul_f32_e32 v12, v13, v12
	v_cvt_pk_bf16_f32 v12, v9, v12
	v_mov_b32_dpp v9, v118 row_ror:1 row_mask:0xf bank_mask:0xf bound_ctrl:1
	v_mov_b32_dpp v13, v118 row_ror:2 row_mask:0xf bank_mask:0xf bound_ctrl:1
	v_mov_b32_dpp v71, v20 row_ror:1 row_mask:0xf bank_mask:0xf bound_ctrl:1
	v_mov_b32_dpp v9, v4 row_shr:1 row_mask:0xf bank_mask:0xf
	v_mul_f32_e32 v9, v116, v9
	v_mov_b32_dpp v13, v4 row_shr:2 row_mask:0xf bank_mask:0xf
	v_fmac_f32_e32 v9, v4, v114
	v_fmac_f32_e32 v9, v110, v13
	v_add_f32_e32 v9, v112, v9
	v_mul_f32_e32 v13, 0xbfb8aa3b, v9
	v_exp_f32_e32 v13, v13
	v_mov_b32_dpp v71, v0 row_shr:1 row_mask:0xf bank_mask:0xf
	v_mov_b32_dpp v20, v20 row_ror:2 row_mask:0xf bank_mask:0xf bound_ctrl:1
	v_mul_f32_e32 v71, v108, v71
	v_add_f32_e32 v13, 1.0, v13
	v_rcp_f32_e32 v13, v13
	v_mov_b32_dpp v20, v0 row_shr:2 row_mask:0xf bank_mask:0xf
	v_fmac_f32_e32 v71, v0, v100
	v_fmac_f32_e32 v71, v98, v20
	v_mul_f32_e32 v9, v9, v13
	v_mov_b32_dpp v13, v119 row_ror:1 row_mask:0xf bank_mask:0xf bound_ctrl:1
	v_add_f32_e32 v20, v102, v71
	v_mul_f32_e32 v9, v20, v9
	v_mov_b32_dpp v13, v5 row_shr:1 row_mask:0xf bank_mask:0xf
	v_mov_b32_dpp v20, v119 row_ror:2 row_mask:0xf bank_mask:0xf bound_ctrl:1
	v_mul_f32_e32 v13, v117, v13
	v_fmac_f32_e32 v13, v5, v115
	v_mov_b32_dpp v20, v5 row_shr:2 row_mask:0xf bank_mask:0xf
	v_fmac_f32_e32 v13, v111, v20
	v_add_f32_e32 v13, v113, v13
	v_mul_f32_e32 v20, 0xbfb8aa3b, v13
	v_exp_f32_e32 v20, v20
	v_mov_b32_dpp v71, v21 row_ror:1 row_mask:0xf bank_mask:0xf bound_ctrl:1
	v_mov_b32_dpp v21, v21 row_ror:2 row_mask:0xf bank_mask:0xf bound_ctrl:1
	v_add_f32_e32 v20, 1.0, v20
	v_mov_b32_dpp v71, v1 row_shr:1 row_mask:0xf bank_mask:0xf
	v_rcp_f32_e32 v20, v20
	v_mul_f32_e32 v71, v109, v71
	v_mov_b32_dpp v21, v1 row_shr:2 row_mask:0xf bank_mask:0xf
	v_fmac_f32_e32 v71, v1, v101
	v_fmac_f32_e32 v71, v99, v21
	v_add_f32_e32 v21, v103, v71
	v_mul_f32_e32 v13, v13, v20
	v_mul_f32_e32 v13, v21, v13
	v_cvt_pk_bf16_f32 v20, v9, v13
	s_waitcnt vmcnt(6)
	s_nop 0
	v_mul_f32_dpp v13, v62, v68 row_shr:1 row_mask:0xf bank_mask:0xf bound_ctrl:1
	v_mov_b32_dpp v9, v62 row_shr:2 row_mask:0xf bank_mask:0xf bound_ctrl:1
	s_waitcnt vmcnt(5)
	v_fmac_f32_e32 v13, v62, v66
	v_fmac_f32_e32 v13, v52, v9
	s_waitcnt vmcnt(4)
	v_add_f32_e32 v9, v64, v13
	v_mul_f32_e32 v13, 0xbfb8aa3b, v9
	v_exp_f32_e32 v13, v13
	s_waitcnt vmcnt(2)
	v_mul_f32_dpp v71, v58, v48 row_shr:1 row_mask:0xf bank_mask:0xf bound_ctrl:1
	v_mov_b32_dpp v21, v58 row_shr:2 row_mask:0xf bank_mask:0xf bound_ctrl:1
	s_waitcnt vmcnt(1)
	v_fmac_f32_e32 v71, v58, v40
	v_add_f32_e32 v13, 1.0, v13
	v_rcp_f32_e32 v13, v13
	v_fmac_f32_e32 v71, v16, v21
	s_waitcnt vmcnt(0)
	v_add_f32_e32 v21, v44, v71
	v_mul_f32_dpp v89, v59, v49 row_shr:1 row_mask:0xf bank_mask:0xf bound_ctrl:1
	v_mul_f32_dpp v71, v63, v69 row_shr:1 row_mask:0xf bank_mask:0xf bound_ctrl:1
	v_mul_f32_e32 v9, v9, v13
	v_mov_b32_dpp v13, v63 row_shr:2 row_mask:0xf bank_mask:0xf bound_ctrl:1
	v_fmac_f32_e32 v71, v63, v67
	v_fmac_f32_e32 v71, v53, v13
	v_add_f32_e32 v13, v65, v71
	v_mul_f32_e32 v71, 0xbfb8aa3b, v13
	v_exp_f32_e32 v71, v71
	v_mul_f32_e32 v9, v21, v9
	v_mov_b32_dpp v21, v59 row_shr:2 row_mask:0xf bank_mask:0xf bound_ctrl:1
	v_fmac_f32_e32 v89, v59, v41
	v_add_f32_e32 v71, 1.0, v71
	v_rcp_f32_e32 v71, v71
	v_fmac_f32_e32 v89, v17, v21
	v_add_f32_e32 v21, v45, v89
	v_mul_f32_e32 v13, v13, v71
	v_mul_f32_e32 v13, v21, v13
	v_cvt_pk_bf16_f32 v95, v9, v13
	s_and_saveexec_b64 s[56:57], s[2:3]
	s_xor_b64 s[56:57], exec, s[56:57]
	s_cbranch_execz .LBB0_1228
	v_mov_b64_e32 v[80:81], s[48:49]
	v_mad_i64_i32 v[80:81], s[58:59], v156, s85, v[80:81]
	v_lshl_add_u64 v[80:81], v[146:147], 1, v[80:81]
	v_mov_b32_e32 v232, v251
	v_mov_b32_e32 v233, v252
	v_mov_b32_e32 v234, v94
	v_mov_b32_e32 v235, v95
	s_nop 1
	v_permlane16_swap_b32_e32 v232, v234
	v_permlane16_swap_b32_e32 v233, v235
	v_lshl_add_u64 v[236:237], v[80:81], 0, v[238:239]
	global_store_dwordx4 v[236:237], v[232:235], off
	s_nop 1
